# v27 + scalar sink load in attention loop (no vmcnt0 at unit top) + path-dependent vmcnt in gMLP loop (prefetch stays in flight)
# speedup vs baseline: 1.0053x; 1.0022x over previous
; __device__ __forceinline__ void attn_load(AttnKV& R, bf16x8 (&q)[8], int au, const bf16_t* Qg, const bf16_t* Kg, const bf16_t* Vg, int tid) {
;     const int wid = tid >> 6, lane = tid & 63, fr = lane & 15, fq = lane >> 4;
;     const int b = au >> 9, blk = (au >> 2) & 127, kvh = au & 3;
;     const int tok0 = b * SEQ + blk * 128;
; #pragma unroll
;     for (int it = 0; it < 4; ++it) { const int c = it * NTHREADS + tid, key = c >> 3, dc = c & 7;
;         u32x4 v = (u32x4){0u, 0u, 0u, 0u};
;         if (blk > 0 || key >= 128) v = *(const u32x4*)(Kg + (size_t)(tok0 - 128 + key) * 256 + kvh * 64 + dc * 8);
; __device__ __forceinline__ void mixer_phase(LAS unsigned char* lds, unsigned char* ws, const float* sinks, const float* bsp, int tid) {
;     ...
;         for (; au < NA; au += G) { const int an = au + G; const bool hn = an < NA;
; #pragma unroll
;             for (int i = 0; i < 8; ++i) qn[i] = q[i];
;             const float sink = sinks[(au & 3) * 4 + (__builtin_amdgcn_readfirstlane(tid >> 6) >> 1)] * 1.4426950408889634f;
;             asm volatile("" :: "v"(sink));
;             if (hn) attn_load(R, qn, an, Qg, Kg, Vg, tid);
.LBB0_553:
	s_add_i32 s61, s10, s22
	s_cmpk_lt_i32 s61, 0x400
	s_cselect_b64 s[50:51], -1, 0
	s_cmpk_gt_i32 s61, 0x3ff
	v_readfirstlane_b32 s6, v212
	s_cselect_b64 s[48:49], -1, 0
	s_and_b32 s11, s55, 12
	s_lshr_b32 s6, s6, 7
	s_add_i32 s6, s6, s11
	s_lshl_b32 s6, s6, 2
	s_load_dword s6, s[40:41], s6
	s_and_b64 vcc, exec, s[48:49]
	s_waitcnt lgkmcnt(0)
	v_mov_b32_e32 v33, s6
	v_mul_f32_e32 v134, 0x3fb8aa3b, v33
	s_cbranch_vccnz .LBB0_562
	s_bfe_u32 s6, s61, 0x70002
	s_add_i32 s7, s54, s19
	s_and_b32 s7, s7, 0xffffc000
	s_lshl_b32 s8, s6, 7
	s_and_b32 s12, s61, 3
	s_or_b32 s13, s8, s7
	s_add_i32 s33, s13, 0xffffff80
	s_lshl_b32 s44, s12, 7
	s_cmp_eq_u32 s6, 0
	v_lshl_add_u64 v[8:9], v[98:99], 0, s[44:45]
	s_cbranch_scc1 .LBB0_556
	v_or_b32_e32 v0, s33, v110
	v_ashrrev_i32_e32 v1, 31, v0
	v_lshlrev_b64 v[0:1], 9, v[0:1]
	v_lshl_add_u64 v[0:1], v[8:9], 0, v[0:1]
	global_load_dwordx4 v[0:3], v[0:1], off
	s_or_b64 s[6:7], s[42:43], exec
	s_branch .LBB0_557

; __device__ __forceinline__ unsigned cvt_pk_bf16(float lo, float hi) { unsigned r; asm volatile("v_cvt_pk_bf16_f32 %0, %1, %2" : "=v"(r) : "v"(lo), "v"(hi)); return r; }
; __device__ __forceinline__ float dot4(const f32x4 a) { return (a[0] * a[0] + a[1] * a[1]) + (a[2] * a[2] + a[3] * a[3]); }
; __device__ __forceinline__ float bf2f(unsigned b) { return __uint_as_float(b << 16); }
; __device__ __forceinline__ void gmlp_compute(LAS unsigned char* lds, int gu, const GmlpCur& C, bf16_t* AO, float* partB, int tid) {
;     ...
;     float ss = 0.f;
; #pragma unroll
;     for (int ct = 0; ct < 8; ++ct) { const int col = g * 128 + 16 * ct + 4 * fq; const u32x2 gw = C.gw[ct];
;         f32x4 v; v[0] = bf2f(gw.x & 0xffffu) * (acc[ct][0] + bias); v[1] = bf2f(gw.x >> 16) * (acc[ct][1] + bias); v[2] = bf2f(gw.y & 0xffffu) * (acc[ct][2] + bias); v[3] = bf2f(gw.y >> 16) * (acc[ct][3] + bias);
;         ss += pg8::dot4(v); u32x2 w; w.x = cvt_pk_bf16(v[0], v[1]); w.y = cvt_pk_bf16(v[2], v[3]);
;         *(u32x2*)(AO + (size_t)row * 2048 + 1024 + col) = w; }
.LBB0_576:
	s_lshr_b32 s6, s6, 2
	s_and_b32 s6, s6, 0x3ffffff0
	s_waitcnt vmcnt(9)
	v_or_b32_e32 v64, s33, v81
	s_waitcnt vmcnt(8)
	v_lshlrev_b32_e32 v70, 16, v103
	v_and_b32_e32 v71, 0xffff0000, v103
	s_cmp_lg_u64 s[8:9], 0
	s_cbranch_scc0 .Lgm_pf
	s_waitcnt vmcnt(0)
	s_branch .Lgm_w
.Lgm_pf:
	s_waitcnt vmcnt(8)
.Lgm_w:
	v_pk_add_f32 v[62:63], v[88:89], v[62:63] op_sel_hi:[0,1]
	v_add_u32_e32 v64, s6, v64
	v_pk_mul_f32 v[62:63], v[62:63], v[70:71]
	v_ashrrev_i32_e32 v65, 31, v64
	v_lshlrev_b32_e32 v68, 16, v102
	v_and_b32_e32 v69, 0xffff0000, v102
	v_pk_add_f32 v[60:61], v[88:89], v[60:61] op_sel_hi:[0,1]
	v_mul_f32_e32 v70, v62, v62
	v_or_b32_e32 v74, s34, v80
	v_lshlrev_b64 v[66:67], 12, v[64:65]
	v_pk_mul_f32 v[60:61], v[60:61], v[68:69]
	v_pk_fma_f32 v[70:71], v[62:63], v[62:63], v[70:71] op_sel_hi:[1,1,0]
	v_cvt_pk_bf16_f32 v72, v60, v61
	v_cvt_pk_bf16_f32 v73, v62, v63
	v_lshlrev_b32_e32 v62, 16, v100
	v_and_b32_e32 v63, 0xffff0000, v100
	v_pk_add_f32 v[56:57], v[88:89], v[56:57] op_sel_hi:[0,1]
	v_lshl_add_u64 v[66:67], s[0:1], 0, v[66:67]
	v_mul_f32_e32 v68, v60, v60
	v_lshlrev_b32_e32 v76, 1, v74
	v_pk_mul_f32 v[56:57], v[56:57], v[62:63]
	v_pk_fma_f32 v[68:69], v[60:61], v[60:61], v[68:69] op_sel_hi:[1,1,0]
	v_lshl_add_u64 v[60:61], v[66:67], 0, v[76:77]
	v_mul_f32_e32 v62, v56, v56
	global_store_dwordx2 v[60:61], v[72:73], off offset:2048
	v_pk_fma_f32 v[62:63], v[56:57], v[56:57], v[62:63] op_sel_hi:[1,1,0]
	v_lshlrev_b32_e32 v66, 16, v101
	v_and_b32_e32 v67, 0xffff0000, v101
	v_pk_add_f32 v[58:59], v[88:89], v[58:59] op_sel_hi:[0,1]
	v_cvt_pk_bf16_f32 v56, v56, v57
	v_pk_mul_f32 v[58:59], v[58:59], v[66:67]
	v_add_f32_e32 v52, v88, v52
	v_cvt_pk_bf16_f32 v57, v58, v59
	global_store_dwordx2 v[60:61], v[56:57], off offset:2080
	v_lshlrev_b32_e32 v56, 16, v98
	v_mul_f32_e32 v66, v58, v58
	v_mul_f32_e32 v57, v52, v56
	v_and_b32_e32 v52, 0xffff0000, v98
	v_add_f32_e32 v53, v88, v53
	v_pk_fma_f32 v[66:67], v[58:59], v[58:59], v[66:67] op_sel_hi:[1,1,0]
	v_mul_f32_e32 v59, v53, v52
	v_lshlrev_b32_e32 v52, 16, v99
	v_add_f32_e32 v53, v88, v54
	v_mul_f32_e32 v53, v53, v52
	v_and_b32_e32 v52, 0xffff0000, v99
	v_add_f32_e32 v54, v88, v55
	v_mul_f32_e32 v76, v54, v52
	v_cvt_pk_bf16_f32 v54, v57, v59
	v_cvt_pk_bf16_f32 v55, v53, v76
	v_add_f32_e32 v52, v88, v49
	v_lshlrev_b32_e32 v49, 16, v97
	v_add_f32_e32 v50, v88, v50
	global_store_dwordx2 v[60:61], v[54:55], off offset:2112
	v_lshlrev_b32_e32 v54, 16, v96
	v_add_f32_e32 v56, v88, v48
	v_mul_f32_e32 v50, v50, v49
	v_and_b32_e32 v49, 0xffff0000, v97
	v_add_f32_e32 v51, v88, v51
	v_mov_b32_e32 v55, v57
	v_and_b32_e32 v48, 0xffff0000, v96
	v_mul_f32_e32 v58, v51, v49
	v_pk_mul_f32 v[72:73], v[56:57], v[54:55]
	v_mov_b32_e32 v57, v59
	v_mov_b32_e32 v55, v59
	v_mov_b32_e32 v49, v53
	v_pk_mul_f32 v[74:75], v[56:57], v[54:55]
	v_pk_mul_f32 v[96:97], v[52:53], v[48:49]
	v_mov_b32_e32 v53, v76
	v_mov_b32_e32 v49, v76
	v_pk_mul_f32 v[98:99], v[52:53], v[48:49]
	v_pk_mul_f32 v[74:75], v[72:73], v[74:75]
	v_pk_fma_f32 v[54:55], v[56:57], v[54:55], v[72:73]
	v_pk_fma_f32 v[48:49], v[52:53], v[48:49], v[96:97]
	v_mov_b32_e32 v75, v55
	v_pk_mul_f32 v[54:55], v[96:97], v[98:99]
	v_mov_b32_e32 v51, v69
	v_mov_b32_e32 v55, v49
	v_mov_b32_e32 v52, v50
	v_mov_b32_e32 v53, v71
	v_pk_add_f32 v[48:49], v[74:75], v[54:55]
	v_pk_mul_f32 v[52:53], v[50:51], v[52:53]
	v_pk_add_f32 v[54:55], v[68:69], v[70:71]
	v_mov_b32_e32 v59, v63
	v_mov_b32_e32 v53, v55
	v_mov_b32_e32 v54, v58
	v_mov_b32_e32 v55, v67
	v_pk_mul_f32 v[54:55], v[58:59], v[54:55]
	v_pk_add_f32 v[56:57], v[62:63], v[66:67]
	v_lshlrev_b32_e32 v51, 16, v95
	v_mov_b32_e32 v55, v57
	v_pk_add_f32 v[52:53], v[52:53], v[54:55]
	v_pk_add_f32 v[40:41], v[88:89], v[40:41] op_sel_hi:[0,1]
	v_pk_add_f32 v[48:49], v[48:49], v[52:53]
	v_cvt_pk_bf16_f32 v52, v72, v96
	v_cvt_pk_bf16_f32 v53, v50, v58
	global_store_dwordx2 v[60:61], v[52:53], off offset:2144
	v_mov_b32_e32 v52, v44
	v_mov_b32_e32 v53, v46
	v_lshlrev_b32_e32 v50, 16, v94
	v_pk_add_f32 v[52:53], v[88:89], v[52:53] op_sel_hi:[0,1]
	v_mov_b32_e32 v46, v45
	v_pk_mul_f32 v[50:51], v[52:53], v[50:51]
	v_and_b32_e32 v53, 0xffff0000, v95
	v_and_b32_e32 v52, 0xffff0000, v94
	v_pk_add_f32 v[44:45], v[88:89], v[46:47] op_sel_hi:[0,1]
	v_pk_mul_f32 v[44:45], v[44:45], v[52:53]
	v_pk_add_f32 v[42:43], v[88:89], v[42:43] op_sel_hi:[0,1]
	v_pk_mul_f32 v[46:47], v[44:45], v[44:45]
	v_cvt_pk_bf16_f32 v44, v50, v44
	v_cvt_pk_bf16_f32 v45, v51, v45
	global_store_dwordx2 v[60:61], v[44:45], off offset:2176
	v_lshlrev_b32_e32 v44, 16, v92
	v_and_b32_e32 v45, 0xffff0000, v92
	v_pk_mul_f32 v[40:41], v[40:41], v[44:45]
	v_pk_fma_f32 v[46:47], v[50:51], v[50:51], v[46:47]
	v_mul_f32_e32 v44, v40, v40
	v_pk_fma_f32 v[44:45], v[40:41], v[40:41], v[44:45] op_sel_hi:[1,1,0]
	v_lshlrev_b32_e32 v50, 16, v93
	v_and_b32_e32 v51, 0xffff0000, v93
	v_cvt_pk_bf16_f32 v40, v40, v41
	v_pk_mul_f32 v[42:43], v[42:43], v[50:51]
	v_add_f32_e32 v36, v88, v36
	v_cvt_pk_bf16_f32 v41, v42, v43
	global_store_dwordx2 v[60:61], v[40:41], off offset:2208
	v_lshlrev_b32_e32 v40, 16, v90
	v_mul_f32_e32 v41, v36, v40
	v_and_b32_e32 v36, 0xffff0000, v90
	v_add_f32_e32 v37, v88, v37
	v_mul_f32_e32 v53, v37, v36
	v_lshlrev_b32_e32 v36, 16, v91
	v_add_f32_e32 v37, v88, v38
	v_mul_f32_e32 v37, v37, v36
	v_and_b32_e32 v36, 0xffff0000, v91
	v_add_f32_e32 v38, v88, v39
	v_mul_f32_e32 v50, v42, v42
	v_mul_f32_e32 v62, v38, v36
	v_add_f32_e32 v36, v88, v33
	v_lshlrev_b32_e32 v33, 16, v87
	v_add_f32_e32 v34, v88, v34
	v_pk_fma_f32 v[50:51], v[42:43], v[42:43], v[50:51] op_sel_hi:[1,1,0]
	v_lshlrev_b32_e32 v42, 16, v86
	v_add_f32_e32 v40, v88, v32
; __device__ __forceinline__ unsigned cvt_pk_bf16(float lo, float hi) { unsigned r; asm volatile("v_cvt_pk_bf16_f32 %0, %1, %2" : "=v"(r) : "v"(lo), "v"(hi)); return r; }
; __device__ __forceinline__ float dot4(const f32x4 a) { return (a[0] * a[0] + a[1] * a[1]) + (a[2] * a[2] + a[3] * a[3]); }
; #define LAS __attribute__((address_space(3)))
; __device__ __forceinline__ float bf2f(unsigned b) { return __uint_as_float(b << 16); }
; __device__ __forceinline__ void gmlp_store_lds(const GmlpIn& R, LAS unsigned char* lds, int tid) {
; #pragma unroll
;     for (int it = 0; it < 2; ++it) { const int task = it * NTHREADS + tid, cc = task & 15, p = task >> 4;
;         const f32x4 pa = R.pa[it], pb = R.pb[it];
;         const float rsa = __builtin_amdgcn_rsqf(((pa[0] + pa[1]) + (pa[2] + pa[3])) * (1.0f / 128.0f) + EPS), rsb = __builtin_amdgcn_rsqf(((pb[0] + pb[1]) + (pb[2] + pb[3])) * (1.0f / 128.0f) + EPS);
; #pragma unroll
;         for (int i = 0; i < 4; ++i) { const unsigned wa = R.a[it][i], wb = R.b[it][i];
;             *(LAS unsigned*)(lds + (cc * 8 + 2 * i) * GT_STRIDE + p * 4) = cvt_pk_bf16(bf2f(wa & 0xffffu) * rsa, bf2f(wb & 0xffffu) * rsb);
;             *(LAS unsigned*)(lds + (cc * 8 + 2 * i + 1) * GT_STRIDE + p * 4) = cvt_pk_bf16(bf2f(wa >> 16) * rsa, bf2f(wb >> 16) * rsb); } }
; }
; __device__ __forceinline__ void gmlp_compute(LAS unsigned char* lds, int gu, const GmlpCur& C, bf16_t* AO, float* partB, int tid) {
;     ...
;     for (int ct = 0; ct < 8; ++ct) { const int col = g * 128 + 16 * ct + 4 * fq; const u32x2 gw = C.gw[ct];
;         f32x4 v; v[0] = bf2f(gw.x & 0xffffu) * (acc[ct][0] + bias); v[1] = bf2f(gw.x >> 16) * (acc[ct][1] + bias); v[2] = bf2f(gw.y & 0xffffu) * (acc[ct][2] + bias); v[3] = bf2f(gw.y >> 16) * (acc[ct][3] + bias);
;         ss += pg8::dot4(v); u32x2 w; w.x = cvt_pk_bf16(v[0], v[1]); w.y = cvt_pk_bf16(v[2], v[3]);
;         *(u32x2*)(AO + (size_t)row * 2048 + 1024 + col) = w; }
;     ss += __shfl_xor(ss, 16); ss += __shfl_xor(ss, 32);
;     partB[(size_t)row * 8 + g] = ss;
	v_mul_f32_e32 v34, v34, v33
	v_and_b32_e32 v33, 0xffff0000, v87
	v_add_f32_e32 v35, v88, v35
	v_mov_b32_e32 v43, v41
	v_cvt_pk_bf16_f32 v38, v41, v53
	v_and_b32_e32 v32, 0xffff0000, v86
	v_mul_f32_e32 v52, v35, v33
	v_pk_mul_f32 v[54:55], v[40:41], v[42:43]
	v_mov_b32_e32 v41, v53
	v_mov_b32_e32 v43, v53
	v_mov_b32_e32 v33, v37
	v_cvt_pk_bf16_f32 v39, v37, v62
	v_pk_mul_f32 v[56:57], v[40:41], v[42:43]
	v_pk_mul_f32 v[58:59], v[36:37], v[32:33]
	v_mov_b32_e32 v37, v62
	v_mov_b32_e32 v33, v62
	v_pk_mul_f32 v[62:63], v[36:37], v[32:33]
	v_pk_mul_f32 v[56:57], v[54:55], v[56:57]
	v_pk_fma_f32 v[40:41], v[40:41], v[42:43], v[54:55]
	v_pk_fma_f32 v[32:33], v[36:37], v[32:33], v[58:59]
	v_mov_b32_e32 v57, v41
	v_pk_mul_f32 v[40:41], v[58:59], v[62:63]
	v_mov_b32_e32 v35, v45
	v_mov_b32_e32 v41, v33
	v_mov_b32_e32 v36, v34
	v_mov_b32_e32 v37, v51
	v_pk_add_f32 v[48:49], v[48:49], v[48:49] op_sel_hi:[0,1]
	v_pk_add_f32 v[46:47], v[46:47], v[46:47] op_sel_hi:[0,1]
	v_pk_add_f32 v[32:33], v[56:57], v[40:41]
	v_pk_mul_f32 v[36:37], v[34:35], v[36:37]
	v_pk_add_f32 v[40:41], v[44:45], v[50:51]
	v_mov_b32_e32 v53, v47
	v_mov_b32_e32 v37, v41
	v_mov_b32_e32 v40, v52
	v_mov_b32_e32 v41, v49
	v_pk_mul_f32 v[40:41], v[52:53], v[40:41]
	v_pk_add_f32 v[42:43], v[46:47], v[48:49]
	v_and_b32_e32 v35, 64, v112
	v_mov_b32_e32 v41, v43
	v_pk_add_f32 v[36:37], v[36:37], v[40:41]
	v_add_u32_e32 v35, 64, v35
	v_pk_add_f32 v[32:33], v[32:33], v[36:37]
	global_store_dwordx2 v[60:61], v[38:39], off offset:2240
	v_add_f32_e32 v32, v32, v33
	v_xor_b32_e32 v33, 16, v112
	v_cmp_lt_i32_e32 vcc, v33, v35
	s_lshl_b32 s6, s19, 2
	s_xor_b32 s13, s13, 1
	v_cndmask_b32_e32 v33, v112, v33, vcc
	v_lshlrev_b32_e32 v33, 2, v33
	ds_bpermute_b32 v33, v33, v32
	s_waitcnt lgkmcnt(0)
	v_add_f32_e32 v36, v32, v33
	v_xor_b32_e32 v32, 32, v112
	v_cmp_lt_i32_e32 vcc, v32, v35
	s_nop 1
	v_cndmask_b32_e32 v32, v112, v32, vcc
	v_lshlrev_b32_e32 v32, 2, v32
	ds_bpermute_b32 v35, v32, v36
	v_cvt_pk_bf16_f32 v32, v54, v58
	v_cvt_pk_bf16_f32 v33, v34, v52
	global_store_dwordx2 v[60:61], v[32:33], off offset:2272
	v_lshlrev_b64 v[32:33], 5, v[64:65]
	v_lshl_add_u64 v[32:33], s[36:37], 0, v[32:33]
	s_waitcnt lgkmcnt(0)
	v_add_f32_e32 v34, v36, v35
	v_lshl_add_u64 v[32:33], v[32:33], 0, s[6:7]
	s_andn2_b64 vcc, exec, s[10:11]
	global_store_dword v[32:33], v34, off
	s_cbranch_vccnz .LBB0_569
	s_waitcnt vmcnt(9)
	v_add_f32_e32 v32, v8, v9
	v_add_f32_e32 v33, v10, v11
	v_add_f32_e32 v32, v32, v33
	v_add_f32_e32 v33, v12, v13
	v_add_f32_e32 v34, v14, v15
	v_add_f32_e32 v33, v33, v34
	v_fmamk_f32 v32, v32, 0x3c000000, v111
	v_fmamk_f32 v33, v33, 0x3c000000, v111
	v_rsq_f32_e32 v32, v32
	v_rsq_f32_e32 v33, v33
	v_lshlrev_b32_e32 v34, 16, v0
	v_lshlrev_b32_e32 v35, 16, v4
	s_mul_i32 s6, s13, 0x8800
	v_mul_f32_e32 v34, v32, v34
	v_mul_f32_e32 v35, v33, v35
	v_cvt_pk_bf16_f32 v34, v34, v35
	v_add_u32_e32 v35, s6, v108
	v_add_u32_e32 v36, v35, v107
	ds_write_b32 v36, v34
	v_and_b32_e32 v34, 0xffff0000, v0
	v_mul_f32_e32 v34, v32, v34
	v_and_b32_e32 v37, 0xffff0000, v4
	v_mul_f32_e32 v37, v33, v37
	v_cvt_pk_bf16_f32 v34, v34, v37
	ds_write_b32 v36, v34 offset:272
	v_lshlrev_b32_e32 v34, 16, v1
	v_mul_f32_e32 v34, v32, v34
	v_lshlrev_b32_e32 v37, 16, v5
	v_mul_f32_e32 v37, v33, v37
	v_cvt_pk_bf16_f32 v34, v34, v37
	ds_write_b32 v36, v34 offset:544
	v_and_b32_e32 v34, 0xffff0000, v1
	v_mul_f32_e32 v34, v32, v34
	v_and_b32_e32 v37, 0xffff0000, v5
	v_mul_f32_e32 v37, v33, v37
	v_cvt_pk_bf16_f32 v34, v34, v37
	ds_write_b32 v36, v34 offset:816
	v_lshlrev_b32_e32 v34, 16, v2
	v_mul_f32_e32 v34, v32, v34
	v_lshlrev_b32_e32 v37, 16, v6
	v_mul_f32_e32 v37, v33, v37
	v_cvt_pk_bf16_f32 v34, v34, v37
	ds_write_b32 v36, v34 offset:1088
	v_and_b32_e32 v34, 0xffff0000, v2
	v_mul_f32_e32 v34, v32, v34
	v_and_b32_e32 v37, 0xffff0000, v6
	v_mul_f32_e32 v37, v33, v37
	v_cvt_pk_bf16_f32 v34, v34, v37
	ds_write_b32 v36, v34 offset:1360
	v_lshlrev_b32_e32 v34, 16, v3
	v_mul_f32_e32 v34, v32, v34
	v_lshlrev_b32_e32 v37, 16, v7
	v_mul_f32_e32 v37, v33, v37
	v_cvt_pk_bf16_f32 v34, v34, v37
	ds_write_b32 v36, v34 offset:1632
	v_and_b32_e32 v34, 0xffff0000, v3
	v_mul_f32_e32 v32, v32, v34
	v_and_b32_e32 v34, 0xffff0000, v7
	v_mul_f32_e32 v33, v33, v34
	v_cvt_pk_bf16_f32 v32, v32, v33
	ds_write_b32 v36, v32 offset:1904
	v_add_f32_e32 v32, v24, v25
	v_add_f32_e32 v33, v26, v27
	v_add_f32_e32 v32, v32, v33
	v_add_f32_e32 v33, v28, v29
	v_add_f32_e32 v34, v30, v31
	v_fmamk_f32 v32, v32, 0x3c000000, v111
	v_add_f32_e32 v33, v33, v34
	v_rsq_f32_e32 v32, v32
	v_fmamk_f32 v33, v33, 0x3c000000, v111
	v_rsq_f32_e32 v33, v33
	v_lshlrev_b32_e32 v34, 16, v16
	v_mul_f32_e32 v34, v32, v34
	v_lshlrev_b32_e32 v36, 16, v20
	v_mul_f32_e32 v36, v33, v36
	v_cvt_pk_bf16_f32 v34, v34, v36
	v_add_u32_e32 v35, v35, v109
	ds_write_b32 v35, v34
	v_and_b32_e32 v34, 0xffff0000, v16
	v_mul_f32_e32 v34, v32, v34
	v_and_b32_e32 v36, 0xffff0000, v20
	v_mul_f32_e32 v36, v33, v36
	v_cvt_pk_bf16_f32 v34, v34, v36
	ds_write_b32 v35, v34 offset:272
	v_lshlrev_b32_e32 v34, 16, v17
	v_mul_f32_e32 v34, v32, v34
	v_lshlrev_b32_e32 v36, 16, v21
	v_mul_f32_e32 v36, v33, v36
	v_cvt_pk_bf16_f32 v34, v34, v36
	ds_write_b32 v35, v34 offset:544
	v_and_b32_e32 v34, 0xffff0000, v17
	v_mul_f32_e32 v34, v32, v34
	v_and_b32_e32 v36, 0xffff0000, v21
	v_mul_f32_e32 v36, v33, v36
	v_cvt_pk_bf16_f32 v34, v34, v36
	ds_write_b32 v35, v34 offset:816
	v_lshlrev_b32_e32 v34, 16, v18
	v_mul_f32_e32 v34, v32, v34
	v_lshlrev_b32_e32 v36, 16, v22
	v_mul_f32_e32 v36, v33, v36
	v_cvt_pk_bf16_f32 v34, v34, v36
	ds_write_b32 v35, v34 offset:1088
	v_and_b32_e32 v34, 0xffff0000, v18
	v_mul_f32_e32 v34, v32, v34
	v_and_b32_e32 v36, 0xffff0000, v22
	v_mul_f32_e32 v36, v33, v36
	v_cvt_pk_bf16_f32 v34, v34, v36
	ds_write_b32 v35, v34 offset:1360
	v_lshlrev_b32_e32 v34, 16, v19
	v_mul_f32_e32 v34, v32, v34
	v_lshlrev_b32_e32 v36, 16, v23
	v_mul_f32_e32 v36, v33, v36
	v_cvt_pk_bf16_f32 v34, v34, v36
	ds_write_b32 v35, v34 offset:1632
	v_and_b32_e32 v34, 0xffff0000, v19
	v_mul_f32_e32 v32, v32, v34
	v_and_b32_e32 v34, 0xffff0000, v23
	v_mul_f32_e32 v33, v33, v34
	v_cvt_pk_bf16_f32 v32, v32, v33
	ds_write_b32 v35, v32 offset:1904
	s_branch .LBB0_569
